# band attention prompt loop: wave-uniform tile-active test shortened to s_cmp + s_cbranch_scc0 (always-true tid mask dropped), 4 dead v_mov_b64 P-fragment copies removed; on top of sw9
# speedup vs baseline: 1.0040x; 1.0012x over previous
; template <int D>
; __device__ __forceinline__ void band_unit(LAS unsigned char* lds, const bf16_t* Kg, const bf16_t* Vg, const int ntile, const bf16_t* Qg, bf16_t* Og, float* ssa, const int nci, const int crel0, const LAS float* tb) {
;     ...
;             bf16x8 kf[8];
; #pragma unroll
;             for (int s8 = 0; s8 < 8; ++s8) kf[s8] = *(const LAS bf16x8*)(st + koff[s8]);
;             asm volatile("s_waitcnt lgkmcnt(0)" : "+v"(kf[0]), "+v"(kf[1]), "+v"(kf[2]), "+v"(kf[3]), "+v"(kf[4]), "+v"(kf[5]), "+v"(kf[6]), "+v"(kf[7]) :: "memory");
;             __builtin_amdgcn_s_setprio(1);
; #pragma unroll
;             for (int s8 = 0; s8 < 8; ++s8) sc = __builtin_amdgcn_mfma_f32_32x32x16_bf16(kf[s8], qf[s8], sc, 0, 0, 0);
;             __builtin_amdgcn_s_setprio(0);
;             s16x4 va[8], vb[8];
;             { const unsigned sb = (unsigned)(size_t)st; VTR8(va, sb + voff[0][0], sb + voff[1][0], sb + voff[0][1], sb + voff[1][1]); VTR8(vb, sb + voff[0][2], sb + voff[1][2], sb + voff[0][3], sb + voff[1][3]); }
;             float pe[16];
; #pragma unroll
;             for (int r = 0; r < 16; ++r) { pe[r] = __builtin_amdgcn_exp2f(sc[r]); lsum += pe[r]; }
;             u32x4 pw0, pw1;
;             pw0.x = cvtpk(pe[0], pe[1]); pw0.y = cvtpk(pe[2], pe[3]); pw0.z = cvtpk(pe[4], pe[5]); pw0.w = cvtpk(pe[6], pe[7]);
;             pw1.x = cvtpk(pe[8], pe[9]); pw1.y = cvtpk(pe[10], pe[11]); pw1.z = cvtpk(pe[12], pe[13]); pw1.w = cvtpk(pe[14], pe[15]);
;             VTRW(8, va, pw0, pw1);
;             const bf16x8 pa0 = __builtin_bit_cast(bf16x8, pw0), pa1 = __builtin_bit_cast(bf16x8, pw1);
;             o[0] = __builtin_amdgcn_mfma_f32_32x32x16_bf16(pa0, VFR2(va[0], va[1]), o[0], 0, 0, 0); o[0] = __builtin_amdgcn_mfma_f32_32x32x16_bf16(pa1, VFR2(va[2], va[3]), o[0], 0, 0, 0);
;             o[1] = __builtin_amdgcn_mfma_f32_32x32x16_bf16(pa0, VFR2(va[4], va[5]), o[1], 0, 0, 0); o[1] = __builtin_amdgcn_mfma_f32_32x32x16_bf16(pa1, VFR2(va[6], va[7]), o[1], 0, 0, 0);
;             VTRW(0, vb, pw0, pw1);
;             o[2] = __builtin_amdgcn_mfma_f32_32x32x16_bf16(pa0, VFR2(vb[0], vb[1]), o[2], 0, 0, 0); o[2] = __builtin_amdgcn_mfma_f32_32x32x16_bf16(pa1, VFR2(vb[2], vb[3]), o[2], 0, 0, 0);
;             o[3] = __builtin_amdgcn_mfma_f32_32x32x16_bf16(pa0, VFR2(vb[4], vb[5]), o[3], 0, 0, 0); o[3] = __builtin_amdgcn_mfma_f32_32x32x16_bf16(pa1, VFR2(vb[6], vb[7]), o[3], 0, 0, 0);
.LBB0_594:
	s_mov_b32 s66, s98
	s_waitcnt lgkmcnt(0)
	s_waitcnt lgkmcnt(0)
	s_setprio 1
	v_mfma_f32_32x32x16_bf16 v[68:83], v[192:195], v[84:87], v[68:83]
	v_mfma_f32_32x32x16_bf16 v[68:83], v[188:191], v[88:91], v[68:83]
	v_mfma_f32_32x32x16_bf16 v[68:83], v[184:187], v[92:95], v[68:83]
	v_mfma_f32_32x32x16_bf16 v[68:83], v[180:183], v[96:99], v[68:83]
	v_mfma_f32_32x32x16_bf16 v[68:83], v[170:173], v[100:103], v[68:83]
	v_mfma_f32_32x32x16_bf16 v[68:83], v[126:129], v[104:107], v[68:83]
	v_mfma_f32_32x32x16_bf16 v[68:83], v[122:125], v[108:111], v[68:83]
	v_mfma_f32_32x32x16_bf16 v[68:83], v[116:119], v[112:115], v[68:83]
	s_setprio 0
	v_add_u32_e32 v116, s66, v152
	v_add_u32_e32 v117, s66, v156
	v_add_u32_e32 v118, s66, v153
	v_add_u32_e32 v119, s66, v157
	ds_read_b64_tr_b16 v[180:181], v116
	ds_read_b64_tr_b16 v[182:183], v117
	ds_read_b64_tr_b16 v[170:171], v116 offset:4096
	ds_read_b64_tr_b16 v[172:173], v117 offset:4096
	ds_read_b64_tr_b16 v[126:127], v118
	ds_read_b64_tr_b16 v[128:129], v119
	ds_read_b64_tr_b16 v[122:123], v118 offset:4096
	ds_read_b64_tr_b16 v[124:125], v119 offset:4096
	v_add_u32_e32 v133, s66, v154
	v_add_u32_e32 v134, s66, v158
	v_add_u32_e32 v135, s66, v155
	v_add_u32_e32 v169, s66, v159
	ds_read_b64_tr_b16 v[192:193], v133
	ds_read_b64_tr_b16 v[194:195], v134
	ds_read_b64_tr_b16 v[188:189], v133 offset:4096
	ds_read_b64_tr_b16 v[190:191], v134 offset:4096
	ds_read_b64_tr_b16 v[184:185], v135
	ds_read_b64_tr_b16 v[186:187], v169
	ds_read_b64_tr_b16 v[116:117], v135 offset:4096
	ds_read_b64_tr_b16 v[118:119], v169 offset:4096
	v_exp_f32_e32 v68, v68
	v_exp_f32_e32 v69, v69
	v_exp_f32_e32 v70, v70
	v_exp_f32_e32 v71, v71
	v_add_f32_e32 v0, v0, v68
	v_exp_f32_e32 v72, v72
	v_add_f32_e32 v0, v69, v0
	v_exp_f32_e32 v73, v73
	v_add_f32_e32 v0, v70, v0
	v_exp_f32_e32 v74, v74
	v_add_f32_e32 v0, v71, v0
	v_exp_f32_e32 v75, v75
	v_add_f32_e32 v0, v72, v0
	v_exp_f32_e32 v76, v76
	v_add_f32_e32 v0, v73, v0
	v_exp_f32_e32 v77, v77
	v_add_f32_e32 v0, v74, v0
	v_exp_f32_e32 v78, v78
	v_add_f32_e32 v0, v75, v0
	v_exp_f32_e32 v79, v79
	v_add_f32_e32 v0, v76, v0
	v_exp_f32_e32 v80, v80
	v_add_f32_e32 v0, v77, v0
	v_exp_f32_e32 v81, v81
	v_add_f32_e32 v0, v78, v0
	v_exp_f32_e32 v82, v82
	v_exp_f32_e32 v83, v83
	v_add_f32_e32 v0, v79, v0
	v_add_f32_e32 v0, v80, v0
	v_add_f32_e32 v0, v81, v0
	v_add_f32_e32 v0, v82, v0
	v_cvt_pk_bf16_f32 v68, v68, v69
	v_cvt_pk_bf16_f32 v69, v70, v71
	v_cvt_pk_bf16_f32 v70, v72, v73
	v_cvt_pk_bf16_f32 v71, v74, v75
	v_cvt_pk_bf16_f32 v72, v76, v77
	v_cvt_pk_bf16_f32 v73, v78, v79
	v_cvt_pk_bf16_f32 v74, v80, v81
	v_cvt_pk_bf16_f32 v75, v82, v83
	v_add_f32_e32 v0, v83, v0
	s_waitcnt lgkmcnt(8)
	s_nop 0
	v_mfma_f32_32x32x16_bf16 v[34:49], v[68:71], v[180:183], v[34:49]
	s_waitcnt lgkmcnt(0)
	v_mfma_f32_32x32x16_bf16 v[50:65], v[68:71], v[126:129], v[50:65]
	v_mfma_f32_32x32x16_bf16 v[18:33], v[68:71], v[192:195], v[18:33]
	v_mfma_f32_32x32x16_bf16 v[2:17], v[68:71], v[184:187], v[2:17]
	v_mfma_f32_32x32x16_bf16 v[34:49], v[72:75], v[170:173], v[34:49]
	v_mfma_f32_32x32x16_bf16 v[50:65], v[72:75], v[122:125], v[50:65]
	v_mfma_f32_32x32x16_bf16 v[18:33], v[72:75], v[188:191], v[18:33]
	v_mfma_f32_32x32x16_bf16 v[2:17], v[72:75], v[116:119], v[2:17]

; #define LAS __attribute__((address_space(3)))
; template <int D>
; __device__ __forceinline__ void band_unit(LAS unsigned char* lds, const bf16_t* Kg, const bf16_t* Vg, const int ntile, const bf16_t* Qg, bf16_t* Og, float* ssa, const int nci, const int crel0, const LAS float* tb) {
;     ...
;         const int kcrel = crel0 + ci - (j >> 1);
;         if (wact && kcrel >= 0 && kcrel <= 8) {
;             const LAS unsigned char* st = lds + (j & (D - 1)) * STG;
;             f32x16 sc;
;             if (kcrel < 3) { const int dbase = 64 * kcrel - 32 * (j & 1) + qb * 32 + l31 - 4 * hi;
; #pragma unroll
;                 for (int r = 0; r < 16; ++r) { int d = dbase - ((r & 3) + 8 * (r >> 2)); d = d > 128 ? 128 : d; sc[r] = tb[d + 128]; } }
;             else {
; #pragma unroll
;                 for (int r = 0; r < 16; ++r) sc[r] = cfar; }
;             bf16x8 kf[8];
; #pragma unroll
;             for (int s8 = 0; s8 < 8; ++s8) kf[s8] = *(const LAS bf16x8*)(st + koff[s8]);
.LBB0_605:
	s_lshr_b32 s66, s66, 1
	s_add_i32 s66, s61, s66
	s_sub_i32 s66, s63, s66
	s_cmp_lt_u32 s66, 9
	s_cbranch_scc0 .LBB0_595
	s_add_i32 s98, s14, 0xfffe4000
	s_and_b32 s98, s98, 0x1c000
	v_add3_u32 v170, s98, v147, v142
	v_add3_u32 v126, s98, v148, v142
	v_add3_u32 v122, s98, v149, v142
	v_add3_u32 v116, s98, v150, v142
	v_add3_u32 v133, s98, v143, v142
	v_add3_u32 v134, s98, v144, v142
	v_add3_u32 v135, s98, v145, v142
	v_add3_u32 v169, s98, v146, v142
	ds_read_b128 v[116:119], v116
	ds_read_b128 v[122:125], v122
	ds_read_b128 v[126:129], v126
	ds_read_b128 v[170:173], v170
	ds_read_b128 v[180:183], v169
	ds_read_b128 v[184:187], v135
	ds_read_b128 v[188:191], v134
	ds_read_b128 v[192:195], v133
	v_mov_b64_e32 v[68:69], v[66:67]
	s_cmp_gt_u32 s66, 2
	v_mov_b32_e32 v69, v66
	v_mov_b32_e32 v70, v66
	v_mov_b32_e32 v71, v66
	v_mov_b32_e32 v72, v66
	v_mov_b32_e32 v73, v66
	v_mov_b32_e32 v74, v66
	v_mov_b32_e32 v75, v66
	v_mov_b32_e32 v76, v66
	v_mov_b32_e32 v77, v66
	v_mov_b32_e32 v78, v66
	v_mov_b32_e32 v79, v66
	v_mov_b32_e32 v80, v66
	v_mov_b32_e32 v81, v66
	v_mov_b32_e32 v82, v66
	v_mov_b32_e32 v83, v66
	s_cbranch_scc1 .LBB0_594
	v_and_or_b32 v68, s65, 32, v151
	v_lshl_or_b32 v69, s66, 6, v67
	v_sub_u32_e32 v76, v69, v68
	v_xad_u32 v68, v68, -1, v69
	v_min_i32_e32 v68, 0x80, v68
	v_lshl_add_u32 v69, v68, 2, s51
	v_min_i32_e32 v68, 0x82, v76
	v_lshl_add_u32 v71, v68, 2, s51
	v_min_i32_e32 v68, 0x83, v76
	v_lshl_add_u32 v72, v68, 2, s51
	v_min_i32_e32 v68, 0x88, v76
	v_lshl_add_u32 v73, v68, 2, s51
	v_min_i32_e32 v68, 0x89, v76
	v_lshl_add_u32 v74, v68, 2, s51
	v_min_i32_e32 v68, 0x8a, v76
	v_min_i32_e32 v70, 0x80, v76
	v_lshl_add_u32 v75, v68, 2, s51
	v_min_i32_e32 v68, 0x8b, v76
	v_lshl_add_u32 v70, v70, 2, s51
	v_lshl_add_u32 v77, v68, 2, s51
	ds_read_b32 v68, v70 offset:512
	ds_read_b32 v69, v69 offset:512
	ds_read_b32 v70, v71 offset:504
	ds_read_b32 v71, v72 offset:500
	ds_read_b32 v72, v73 offset:480
	ds_read_b32 v73, v74 offset:476
	ds_read_b32 v74, v75 offset:472
	ds_read_b32 v75, v77 offset:468
	v_min_i32_e32 v77, 0x90, v76
	v_min_i32_e32 v78, 0x91, v76
	v_min_i32_e32 v79, 0x92, v76
	v_min_i32_e32 v80, 0x93, v76
	v_min_i32_e32 v81, 0x98, v76
	v_min_i32_e32 v82, 0x99, v76
	v_min_i32_e32 v83, 0x9a, v76
	v_lshl_add_u32 v77, v77, 2, s51
	v_lshl_add_u32 v78, v78, 2, s51
	v_lshl_add_u32 v79, v79, 2, s51
	v_lshl_add_u32 v80, v80, 2, s51
	v_lshl_add_u32 v81, v81, 2, s51
	v_lshl_add_u32 v82, v82, 2, s51
	v_lshl_add_u32 v83, v83, 2, s51
	v_min_i32_e32 v76, 0x9b, v76
	v_lshl_add_u32 v244, v76, 2, s51
	ds_read_b32 v76, v77 offset:448
	ds_read_b32 v77, v78 offset:444
	ds_read_b32 v78, v79 offset:440
	ds_read_b32 v79, v80 offset:436
	ds_read_b32 v80, v81 offset:416
	ds_read_b32 v81, v82 offset:412
	ds_read_b32 v82, v83 offset:408
	ds_read_b32 v83, v244 offset:404
	s_branch .LBB0_594
